# v38: v37 + sliding-window items skip the 32-element mask on tiles that lie wholly inside the window for all rows of the wave (wave-uniform bound test)
# baseline (speedup 1.0000x reference)
; template <int PM> DI void attn_phase(const Params& p, int l, char* smem, int* s_item, int wv, int cidx) {
;     ...
;     const int tq0 = qt * 256 + w * 32;
;     const int tq = tq0 + l31;
;     const int qrow = tq0 >> 6, qcol = tq & 63;
;     const int kr0 = min(max(qrow - 4, 0), 24);
;     const int cstart = min(max(qcol - 8, 0), 48);
;     if (mode == 2) {
;       if (tid < 465) rpb_s[tid] = p.rpb[(l * 4 + head) * 465 + tid] * LOG2E;
;     }
;     {
;       const u16* gsrc = p.P + (size_t)(Rb + (isctx ? 0 : 256) + qt * 256 + (tid >> 4)) * INW + 5120 + mixer * 512 + head * 128 + (tid & 15) * 8;
;       u32x4 gt[8];
; #pragma unroll
;       for (int j = 0; j < 8; ++j) gt[j] = *(const u32x4*)(gsrc + (size_t)j * 32 * INW);
; #pragma unroll
;       for (int j = 0; j < 8; ++j) *(u32x4*)(gate_s + ((tid >> 4) + 32 * j) * 264 + (tid & 15) * 16) = gt[j];
;     ...
;               const int rbase = (kr - qrow + 7) * 31 + (15 - qcol);
; #pragma unroll
;               for (int kb = 0; kb < 2; ++kb)
; #pragma unroll
;                 for (int e = 0; e < 16; ++e) {
;                   const int kidx = kb * 32 + (e & 3) + 8 * (e >> 2) + 4 * h;
;                   const int dc = kidx - cstart;
;                   const bool valid = dc >= 0 && dc < 16;
;                   const float bias = rpb_s[valid ? rbase + kidx : 0];
;                   sacc[kb][e] = valid ? sacc[kb][e] + bias : -1e30f;
.LBB0_406:
	s_or_b64 exec, exec, s[2:3]
	v_readlane_b32 s2, v254, 57
	s_add_i32 s88, s18, s2
	s_ashr_i32 s82, s88, 6
	s_max_i32 s2, s82, 4
	s_add_i32 s2, s2, -4
	s_xor_b64 s[78:79], s[14:15], -1
	s_add_i32 s81, s80, s11
	s_min_u32 s83, s2, 24
	s_and_b32 s84, s7, 3
	s_and_b64 s[0:1], exec, s[0:1]
	s_cselect_b32 s0, 0, 0x100
	s_mulk_i32 s84, 0x900
	s_add_i32 s0, s18, s0
	v_readlane_b32 s36, v253, 21
	s_add_i32 s2, s0, s84
	v_readlane_b32 s50, v253, 35
	v_readlane_b32 s51, v253, 36
	v_add_u32_e32 v0, s2, v239
	s_movk_i32 s22, 0x3800
	v_mov_b64_e32 v[14:15], s[50:51]
	v_mad_i64_i32 v[2:3], s[0:1], v0, s22, v[14:15]
	s_mov_b32 s17, s21
	s_lshl_b32 s16, s86, 10
	v_lshl_add_u64 v[2:3], v[2:3], 0, s[16:17]
	s_lshl_b32 s0, s20, 1
	s_mov_b32 s1, s21
	v_lshl_add_u64 v[2:3], v[2:3], 0, s[0:1]
	v_mov_b32_e32 v205, v1
	v_lshl_add_u64 v[60:61], v[2:3], 0, v[204:205]
	s_movk_i32 s3, 0x2000
	v_add_co_u32_e32 v2, vcc, s3, v60
	s_mov_b32 s3, 0x72000
	s_nop 0
	v_addc_co_u32_e32 v3, vcc, 0, v61, vcc
	v_add_co_u32_e32 v6, vcc, s3, v60
	s_mov_b32 s3, 0xe2000
	s_nop 0
	v_addc_co_u32_e32 v7, vcc, 0, v61, vcc
	v_add_co_u32_e32 v10, vcc, s3, v60
	s_mov_b32 s3, 0x152000
	s_nop 0
	v_addc_co_u32_e32 v11, vcc, 0, v61, vcc
	v_add_co_u32_e32 v48, vcc, s3, v60
	s_mov_b32 s3, 0x1c2000
	s_nop 0
	v_addc_co_u32_e32 v49, vcc, 0, v61, vcc
	v_add_co_u32_e32 v52, vcc, s3, v60
	s_mov_b32 s3, 0x232000
	s_nop 0
	v_addc_co_u32_e32 v53, vcc, 0, v61, vcc
	v_add_co_u32_e32 v56, vcc, s3, v60
	s_mov_b32 s3, 0x2a2000
	s_nop 0
	v_addc_co_u32_e32 v57, vcc, 0, v61, vcc
	v_add_co_u32_e32 v62, vcc, s3, v60
	s_mov_b32 s3, 0x312000
	s_nop 0
	v_addc_co_u32_e32 v63, vcc, 0, v61, vcc
	v_add_co_u32_e32 v64, vcc, s3, v60
	global_load_dwordx4 v[16:19], v[2:3], off offset:2048
	s_nop 0
	global_load_dwordx4 v[20:23], v[6:7], off offset:2048
	v_addc_co_u32_e32 v65, vcc, 0, v61, vcc
	global_load_dwordx4 v[24:27], v[10:11], off offset:2048
	s_nop 0
	global_load_dwordx4 v[28:31], v[48:49], off offset:2048
	s_nop 0
	global_load_dwordx4 v[32:35], v[52:53], off offset:2048
	s_nop 0
	global_load_dwordx4 v[36:39], v[56:57], off offset:2048
	s_nop 0
	global_load_dwordx4 v[40:43], v[62:63], off offset:2048
	s_nop 0
	global_load_dwordx4 v[44:47], v[64:65], off offset:2048
	v_readlane_b32 s14, v254, 61
	v_readlane_b32 s15, v254, 62
	s_and_b64 s[14:15], s[14:15], exec
	v_add_u32_e32 v68, s2, v241
	s_cselect_b32 s13, 2, 1
	s_lshl_b32 s2, s20, 2
	v_ashrrev_i32_e32 v69, 31, v68
	s_cmp_gt_i32 s81, 1
	v_lshlrev_b64 v[70:71], 11, v[68:69]
	s_cselect_b64 s[14:15], -1, 0
	s_mov_b32 s3, s21
	v_lshl_add_u64 v[70:71], s[92:93], 0, v[70:71]
	v_writelane_b32 v255, s14, 1
	s_cmp_gt_i32 s81, 0
	v_lshl_add_u64 v[70:71], v[70:71], 0, s[2:3]
	v_writelane_b32 v255, s15, 2
	s_cselect_b64 s[2:3], -1, 0
	v_writelane_b32 v255, s2, 3
	v_bitop3_b32 v205, s88, 63, v240 bitop3:0xc8
	v_sub_u32_e64 v0, v205, 8 clamp
	v_writelane_b32 v255, s3, 4
	s_add_i32 s2, s13, -1
	v_writelane_b32 v255, s13, 5
	s_cmp_eq_u32 s86, 1
	v_min_u32_e32 v0, 48, v0
	v_writelane_b32 v255, s2, 6
	s_cselect_b64 s[2:3], -1, 0
	s_mov_b32 s7, s21
	v_writelane_b32 v255, s2, 7
	s_mov_b32 s9, s21
	s_lshl_b64 s[96:97], s[6:7], 1
	v_writelane_b32 v255, s3, 8
	v_readlane_b32 s37, v253, 22
	v_readlane_b32 s38, v253, 23
	v_readlane_b32 s39, v253, 24
	v_readlane_b32 s40, v253, 25
	v_readlane_b32 s41, v253, 26
	v_sub_u32_e32 v6, v198, v0
	v_mad_i64_i32 v[4:5], s[2:3], v68, s22, v[14:15]
	v_cmp_gt_u32_e64 s[6:7], 16, v6
	v_sub_u32_e32 v6, v248, v0
	v_lshl_add_u64 v[4:5], s[8:9], 1, v[4:5]
	v_cmp_gt_u32_e64 s[8:9], 16, v6
	v_add_u32_e32 v6, 8, v198
	v_sub_u32_e32 v10, v6, v0
	v_add_u32_e32 v6, 9, v198
	v_sub_u32_e32 v11, v6, v0
	v_add_u32_e32 v6, 10, v198
	v_sub_u32_e32 v12, v6, v0
	v_add_u32_e32 v6, 11, v198
	v_sub_u32_e32 v13, v6, v0
	v_add_u32_e32 v6, 16, v198
	v_sub_u32_e32 v14, v6, v0
	v_add_u32_e32 v6, 17, v198
	v_sub_u32_e32 v15, v6, v0
	v_add_u32_e32 v6, 18, v198
	v_sub_u32_e32 v48, v6, v0
	v_add_u32_e32 v6, 19, v198
	v_sub_u32_e32 v49, v6, v0
	v_add_u32_e32 v6, 24, v198
	v_sub_u32_e32 v50, v6, v0
	v_add_u32_e32 v6, 25, v198
	v_sub_u32_e32 v51, v6, v0
	v_add_u32_e32 v6, 26, v198
	v_sub_u32_e32 v52, v6, v0
	v_add_u32_e32 v6, 27, v198
	v_sub_u32_e32 v53, v6, v0
	v_add_u32_e32 v6, 32, v198
	v_sub_u32_e32 v54, v6, v0
	v_add_u32_e32 v6, 33, v198
	v_sub_u32_e32 v55, v6, v0
	v_add_u32_e32 v6, 34, v198
	v_sub_u32_e32 v56, v6, v0
	v_add_u32_e32 v6, 35, v198
	v_readlane_b32 s42, v253, 27
	v_readlane_b32 s43, v253, 28
	v_readlane_b32 s44, v253, 29
	v_readlane_b32 s45, v253, 30
	v_readlane_b32 s46, v253, 31
	v_readlane_b32 s47, v253, 32
	v_readlane_b32 s48, v253, 33
	v_readlane_b32 s49, v253, 34
	v_sub_u32_e32 v57, v6, v0
; template <int PM> DI void attn_phase(const Params& p, int l, char* smem, int* s_item, int wv, int cidx) {
;     ...
;         const u16* base = p.P + (size_t)(Rb + trow) * INW + tch * 8;
; #pragma unroll
;         for (int j = 0; j < 2; ++j) {
;           kst[j] = *(const u32x4*)(base + (size_t)j * 32 * INW + koff);
;           vst[j] = *(const u32x4*)(base + (size_t)j * 32 * INW + voff);
;         }
; #pragma unroll
;         for (int j = 0; j < 2; ++j) {
;           *(u32x4*)(Kb0 + (trow + 32 * j) * 272 + tch * 16) = kst[j];
;           *(u32x4*)(Vb0 + (trow + 32 * j) * 320 + tch * 16) = vst[j];
;         }
;         const int R1 = (1 < nplain) ? Rb + 64 : Rb + 256 + local_t0 + 64 * (1 - nplain);
;         const u16* b1 = p.P + (size_t)(R1 + trow) * INW + tch * 8;
;     ...
;               const int dbase = tpos - tq + 4 * h;
; #pragma unroll
;               for (int kb = 0; kb < 2; ++kb)
; #pragma unroll
;                 for (int e = 0; e < 16; ++e) {
;                   const int d = dbase + kb * 32 + (e & 3) + 8 * (e >> 2);
;                   sacc[kb][e] = (d <= 128 && d >= -128) ? sacc[kb][e] : -1e30f;
	v_add_u32_e32 v6, 40, v198
	s_mov_b32 s11, s21
	s_ashr_i32 s13, s12, 31
	v_readlane_b32 s36, v253, 5
	v_sub_u32_e32 v58, v6, v0
	v_add_u32_e32 v6, 41, v198
	s_add_i32 s87, s88, 0xffffff80
	s_addk_i32 s88, 0x9f
	s_lshl_b64 s[76:77], s[10:11], 1
	s_lshl_b64 s[2:3], s[12:13], 2
	v_readlane_b32 s46, v253, 15
	v_sub_u32_e32 v59, v6, v0
	v_add_u32_e32 v6, 42, v198
	v_readlane_b32 s47, v253, 16
	s_add_u32 s2, s46, s2
	v_sub_u32_e32 v60, v6, v0
	v_add_u32_e32 v6, 43, v198
	s_addc_u32 s3, s47, s3
	v_sub_u32_e32 v61, v6, v0
	v_add_u32_e32 v6, 48, v198
	v_lshlrev_b64 v[2:3], 12, v[68:69]
	v_writelane_b32 v255, s2, 9
	v_sub_u32_e32 v62, v6, v0
	v_add_u32_e32 v6, 49, v198
	v_writelane_b32 v255, s3, 10
	v_lshl_add_u64 v[2:3], s[56:57], 0, v[2:3]
	s_mov_b32 s3, s21
	v_sub_u32_e32 v63, v6, v0
	v_add_u32_e32 v6, 50, v198
	v_add_u32_e32 v72, s84, v239
	v_writelane_b32 v254, s2, 59
	v_lshl_add_u64 v[2:3], v[2:3], 0, s[16:17]
	v_sub_u32_e32 v64, v6, v0
	v_add_u32_e32 v6, 51, v198
	v_writelane_b32 v254, s3, 60
	v_lshl_add_u64 v[2:3], v[2:3], 0, s[0:1]
	v_sub_u32_e32 v65, v6, v0
	v_add_u32_e32 v6, 56, v198
	v_lshl_add_u64 v[208:209], v[200:201], 1, v[4:5]
	v_mad_i64_i32 v[4:5], s[0:1], v72, s22, v[202:203]
	s_mov_b64 s[2:3], 0x70000
	v_add_u32_e32 v73, 64, v72
	v_sub_u32_e32 v66, v6, v0
	v_add_u32_e32 v6, 57, v198
	v_lshl_add_u64 v[210:211], v[4:5], 0, s[96:97]
	v_lshl_add_u64 v[212:213], v[4:5], 0, s[76:77]
	v_lshl_add_u64 v[4:5], v[4:5], 0, s[2:3]
	v_sub_u32_e32 v67, v6, v0
	v_add_u32_e32 v6, 58, v198
	v_lshl_add_u64 v[214:215], v[4:5], 0, s[96:97]
	v_lshl_add_u64 v[216:217], v[4:5], 0, s[76:77]
	v_mad_i64_i32 v[4:5], s[0:1], v73, s22, v[202:203]
	v_sub_u32_e32 v68, v6, v0
	v_add_u32_e32 v6, 59, v198
	s_lshl_b32 s0, s80, 6
	v_readlane_b32 s37, v253, 6
	v_readlane_b32 s38, v253, 7
	v_readlane_b32 s39, v253, 8
	v_readlane_b32 s40, v253, 9
	v_readlane_b32 s41, v253, 10
	v_readlane_b32 s42, v253, 11
	v_readlane_b32 s43, v253, 12
	v_readlane_b32 s44, v253, 13
	v_readlane_b32 s45, v253, 14
	v_readlane_b32 s48, v253, 17
	v_readlane_b32 s49, v253, 18
	v_readlane_b32 s50, v253, 19
	v_readlane_b32 s51, v253, 20
	v_sub_u32_e32 v8, v249, v0
	v_sub_u32_e32 v9, v250, v0
	v_sub_u32_e32 v0, v6, v0
	v_lshl_add_u64 v[6:7], v[4:5], 0, s[2:3]
	s_sub_i32 s0, s19, s0
	v_lshl_add_u64 v[206:207], v[198:199], 2, v[70:71]
	s_movk_i32 s85, 0x3800
	s_mov_b64 s[98:99], 0x70000
	v_lshl_add_u64 v[218:219], v[6:7], 0, s[76:77]
	v_lshl_add_u64 v[220:221], v[6:7], 0, s[96:97]
	v_lshl_add_u64 v[222:223], v[4:5], 0, s[76:77]
	v_lshl_add_u64 v[224:225], v[4:5], 0, s[96:97]
	v_lshl_add_u64 v[226:227], v[198:199], 1, v[2:3]
	v_writelane_b32 v255, s0, 11
	v_subrev_u32_e32 v228, s18, v197
	s_nop 1
	v_readlane_b32 s100, v228, 0
	v_readlane_b32 s101, v228, 31
	v_readlane_b32 s32, v228, 32
	v_readlane_b32 vcc_lo, v228, 63
	s_max_i32 s90, s100, s101
	s_min_i32 s101, s100, s101
	s_max_i32 s100, s32, vcc_lo
	s_min_i32 s32, s32, vcc_lo
	s_max_i32 s100, s100, s90
	s_min_i32 s101, s101, s32
	s_add_i32 s90, s84, 0x180
	v_mov_b32_e32 v229, 0
	s_mov_b32 s91, 0
	v_cmp_gt_u32_e64 s[10:11], 16, v8
	v_cmp_gt_u32_e64 s[12:13], 16, v9
	v_cmp_gt_u32_e64 s[14:15], 16, v10
	v_cmp_gt_u32_e64 s[16:17], 16, v11
	v_cmp_gt_u32_e64 s[18:19], 16, v12
	v_cmp_gt_u32_e64 s[20:21], 16, v13
	v_cmp_gt_u32_e64 s[22:23], 16, v14
	v_cmp_gt_u32_e64 s[24:25], 16, v15
	v_cmp_gt_u32_e64 s[26:27], 16, v48
	v_cmp_gt_u32_e64 s[28:29], 16, v49
	v_cmp_gt_u32_e64 s[30:31], 16, v50
	v_cmp_gt_u32_e64 s[34:35], 16, v51
	v_cmp_gt_u32_e64 s[36:37], 16, v52
	v_cmp_gt_u32_e64 s[38:39], 16, v53
	v_cmp_gt_u32_e64 s[40:41], 16, v54
	v_cmp_gt_u32_e64 s[42:43], 16, v55
	v_cmp_gt_u32_e64 s[44:45], 16, v56
	v_cmp_gt_u32_e64 s[46:47], 16, v57
	v_cmp_gt_u32_e64 s[48:49], 16, v58
	v_cmp_gt_u32_e64 s[50:51], 16, v59
	v_cmp_gt_u32_e64 s[52:53], 16, v60
	v_cmp_gt_u32_e64 s[54:55], 16, v61
	v_cmp_gt_u32_e64 s[56:57], 16, v62
	v_cmp_gt_u32_e64 s[58:59], 16, v63
	v_cmp_gt_u32_e64 s[60:61], 16, v64
	v_cmp_gt_u32_e64 s[62:63], 16, v65
	v_cmp_gt_u32_e64 s[64:65], 16, v66
	v_cmp_gt_u32_e64 s[66:67], 16, v67
	v_cmp_gt_u32_e64 s[68:69], 16, v68
	v_cmp_gt_u32_e64 s[70:71], 16, v0
	s_waitcnt vmcnt(7)
	ds_write_b128 v251, v[16:19]
	s_waitcnt vmcnt(6)
	ds_write_b128 v251, v[20:23] offset:8448
	s_waitcnt vmcnt(5)
	ds_write_b128 v251, v[24:27] offset:16896
	s_waitcnt vmcnt(4)
	ds_write_b128 v251, v[28:31] offset:25344
	s_waitcnt vmcnt(3)
	ds_write_b128 v251, v[32:35] offset:33792
	s_waitcnt vmcnt(2)
	ds_write_b128 v251, v[36:39] offset:42240
	s_waitcnt vmcnt(1)
	ds_write_b128 v251, v[40:43] offset:50688
	s_waitcnt vmcnt(0)
	ds_write_b128 v251, v[44:47] offset:59136
	s_branch .LBB0_409

; template <int PM> DI void attn_phase(const Params& p, int l, char* smem, int* s_item, int wv, int cidx) {
;     ...
;             if (mode == 1) {
;               const int dbase = tpos - tq + 4 * h;
; #pragma unroll
;               for (int kb = 0; kb < 2; ++kb)
; #pragma unroll
;                 for (int e = 0; e < 16; ++e) {
;                   const int d = dbase + kb * 32 + (e & 3) + 8 * (e >> 2);
;                   sacc[kb][e] = (d <= 128 && d >= -128) ? sacc[kb][e] : -1e30f;
;                 }
.LBB0_509:
	s_and_b64 vcc, exec, s[0:1]
	s_cbranch_vccz .LBB0_511
	s_add_i32 vcc_lo, s92, s101
	s_addk_i32 vcc_lo, 0x80
	s_add_i32 vcc_hi, s92, s100
	s_addk_i32 vcc_hi, 0xbb
	s_cmp_lt_u32 vcc_hi, s33
	s_cbranch_scc0 .Lwm_mask
	s_cmp_le_u32 vcc_lo, vcc_hi
	s_cbranch_scc1 .LBB0_512
.Lwm_mask:
	v_add_u32_e32 v0, s92, v228
	s_waitcnt lgkmcnt(2)
	v_add_u32_e32 v2, 0x80, v0
	v_cmp_gt_u32_e32 vcc, s33, v2
	v_add_u32_e32 v2, 0x81, v0
	s_nop 0
	v_cndmask_b32_e32 v48, v237, v16, vcc
	v_cmp_gt_u32_e32 vcc, s33, v2
	v_add_u32_e32 v2, 0x82, v0
	s_nop 0
	v_cndmask_b32_e32 v49, v237, v17, vcc
	v_cmp_gt_u32_e32 vcc, s33, v2
	v_add_u32_e32 v2, 0x83, v0
	s_nop 0
	v_cndmask_b32_e32 v50, v237, v18, vcc
	v_cmp_gt_u32_e32 vcc, s33, v2
	v_add_u32_e32 v2, 0x88, v0
	s_nop 0
	v_cndmask_b32_e32 v51, v237, v19, vcc
	v_cmp_gt_u32_e32 vcc, s33, v2
	v_add_u32_e32 v2, 0x89, v0
	s_nop 0
	v_cndmask_b32_e32 v52, v237, v20, vcc
	v_cmp_gt_u32_e32 vcc, s33, v2
	v_add_u32_e32 v2, 0x8a, v0
	s_nop 0
	v_cndmask_b32_e32 v53, v237, v21, vcc
	v_cmp_gt_u32_e32 vcc, s33, v2
	v_add_u32_e32 v2, 0x8b, v0
	s_nop 0
	v_cndmask_b32_e32 v54, v237, v22, vcc
	v_cmp_gt_u32_e32 vcc, s33, v2
	v_add_u32_e32 v2, 0x90, v0
	s_nop 0
	v_cndmask_b32_e32 v55, v237, v23, vcc
	v_cmp_gt_u32_e32 vcc, s33, v2
	v_add_u32_e32 v2, 0x91, v0
	s_nop 0
	v_cndmask_b32_e32 v56, v237, v24, vcc
	v_cmp_gt_u32_e32 vcc, s33, v2
	v_add_u32_e32 v2, 0x92, v0
	s_nop 0
	v_cndmask_b32_e32 v57, v237, v25, vcc
	v_cmp_gt_u32_e32 vcc, s33, v2
	v_add_u32_e32 v2, 0x93, v0
	s_nop 0
	v_cndmask_b32_e32 v58, v237, v26, vcc
	v_cmp_gt_u32_e32 vcc, s33, v2
	v_add_u32_e32 v2, 0x98, v0
	s_nop 0
	v_cndmask_b32_e32 v59, v237, v27, vcc
	v_cmp_gt_u32_e32 vcc, s33, v2
	v_add_u32_e32 v2, 0x99, v0
	s_nop 0
	v_cndmask_b32_e32 v60, v237, v28, vcc
	v_cmp_gt_u32_e32 vcc, s33, v2
	v_add_u32_e32 v2, 0x9a, v0
	s_nop 0
	v_cndmask_b32_e32 v61, v237, v29, vcc
	v_cmp_gt_u32_e32 vcc, s33, v2
	v_add_u32_e32 v2, 0x9b, v0
	s_nop 0
	v_cndmask_b32_e32 v62, v237, v30, vcc
	v_cmp_gt_u32_e32 vcc, s33, v2
	v_add_u32_e32 v2, 0xa0, v0
	s_nop 0
	v_cndmask_b32_e32 v63, v237, v31, vcc
	v_cmp_gt_u32_e32 vcc, s33, v2
	v_add_u32_e32 v2, 0xa1, v0
	s_nop 0
	v_cndmask_b32_e32 v64, v237, v32, vcc
	v_cmp_gt_u32_e32 vcc, s33, v2
	v_add_u32_e32 v2, 0xa2, v0
	s_nop 0
	v_cndmask_b32_e32 v65, v237, v33, vcc
	v_cmp_gt_u32_e32 vcc, s33, v2
	v_add_u32_e32 v2, 0xa3, v0
	s_nop 0
	v_cndmask_b32_e32 v66, v237, v34, vcc
	v_cmp_gt_u32_e32 vcc, s33, v2
	v_add_u32_e32 v2, 0xa8, v0
	s_nop 0
	v_cndmask_b32_e32 v67, v237, v35, vcc
	v_cmp_gt_u32_e32 vcc, s33, v2
	v_add_u32_e32 v2, 0xa9, v0
	s_nop 0
	v_cndmask_b32_e32 v68, v237, v36, vcc
	v_cmp_gt_u32_e32 vcc, s33, v2
	v_add_u32_e32 v2, 0xaa, v0
	s_nop 0
	v_cndmask_b32_e32 v69, v237, v37, vcc
	v_cmp_gt_u32_e32 vcc, s33, v2
	v_add_u32_e32 v2, 0xab, v0
	s_nop 0
	v_cndmask_b32_e32 v70, v237, v38, vcc
	v_cmp_gt_u32_e32 vcc, s33, v2
	v_add_u32_e32 v2, 0xb0, v0
	s_nop 0
	v_cndmask_b32_e32 v71, v237, v39, vcc
	v_cmp_gt_u32_e32 vcc, s33, v2
	v_add_u32_e32 v2, 0xb1, v0
	s_nop 0
	v_cndmask_b32_e32 v72, v237, v40, vcc
	v_cmp_gt_u32_e32 vcc, s33, v2
	v_add_u32_e32 v2, 0xb2, v0
	s_nop 0
	v_cndmask_b32_e32 v73, v237, v41, vcc
	v_cmp_gt_u32_e32 vcc, s33, v2
	v_add_u32_e32 v2, 0xb3, v0
	s_nop 0
	v_cndmask_b32_e32 v74, v237, v42, vcc
	v_cmp_gt_u32_e32 vcc, s33, v2
	v_add_u32_e32 v2, 0xb8, v0
	s_nop 0
	v_cndmask_b32_e32 v75, v237, v43, vcc
	v_cmp_gt_u32_e32 vcc, s33, v2
	v_add_u32_e32 v2, 0xb9, v0
	s_nop 0
	v_cndmask_b32_e32 v76, v237, v44, vcc
	v_cmp_gt_u32_e32 vcc, s33, v2
	v_add_u32_e32 v2, 0xba, v0
	v_add_u32_e32 v0, 0xbb, v0
	v_cndmask_b32_e32 v77, v237, v45, vcc
	v_cmp_gt_u32_e32 vcc, s33, v2
	s_nop 1
	v_cndmask_b32_e32 v78, v237, v46, vcc
	v_cmp_gt_u32_e32 vcc, s33, v0
	s_nop 1
	v_cndmask_b32_e32 v79, v237, v47, vcc
